# ret/hgrn hand-written final stages, each padded in place so every other instruction keeps its address
# speedup vs baseline: 1.0079x; 1.0013x over previous
; __device__ __forceinline__ bf16_t f2bf(float f) { return (bf16_t)(pk2(f, 0.f) & 0xffffu); }
; __device__ __forceinline__ float fexp(float x) { return __expf(x); }
; #define LBAR() do { asm volatile("s_waitcnt lgkmcnt(0)" ::: "memory"); __builtin_amdgcn_s_barrier(); asm volatile("" ::: "memory"); } while (0)
; __device__ __forceinline__ void hgrn_unit(const Ctx& X, LAS unsigned char* hl, int b, int c, int h, int tid_h, int w4, int lane, int layer) {
;     ...
; #pragma unroll
;         for (int ct = 0; ct < 4; ++ct)
; #pragma unroll
;             for (int j = 0; j < 4; ++j) { const int ii = 16 * I + 4 * q + j, col = 16 * ct + r;
;                 QT[ii * LT + col] = f2bf((ct <= I && ii >= col) ? acc[ct][j] : 0.f); }
;     }
;     LBAR();
;     {
; #pragma unroll
;         for (int e = 0; e < 16; ++e) { VT[(ds + e) * LT + i] = f2bf(vv[e]); KDT[(ds + e) * LT + i] = f2bf(kk[e] * fexp(G63[e] - Gi[e])); }
;     }
.LBB0_317:
	v_ashrrev_i32_e32 v96, 4, v130
	v_lshl_add_u32 v98, v96, 2, s39
	v_cmp_ge_i32_e32 vcc, v98, v91
	v_lshlrev_b32_e32 v99, 1, v91
	v_mul_lo_u32 v100, v98, s44
	v_cndmask_b32_e32 v18, 0, v18, vcc
	s_waitcnt lgkmcnt(0)
	v_cvt_pk_bf16_f32 v18, v18, v157
	v_add3_u32 v74, v74, v99, v100
	ds_write_b16 v74, v18
	v_or_b32_e32 v18, 1, v98
	v_cmp_ge_i32_e32 vcc, v18, v91
	v_or_b32_e32 v99, 16, v91
	v_readlane_b32 s6, v252, 48
	v_cndmask_b32_e32 v19, 0, v19, vcc
	v_cvt_pk_bf16_f32 v19, v19, v157
	ds_write_b16 v74, v19 offset:144
	v_or_b32_e32 v19, 2, v98
	v_cmp_ge_i32_e32 vcc, v19, v91
	v_readlane_b32 s7, v252, 49
	v_or_b32_e32 v22, 48, v91
	v_cndmask_b32_e32 v20, 0, v20, vcc
	v_cvt_pk_bf16_f32 v20, v20, v157
	ds_write_b16 v74, v20 offset:288
	v_or_b32_e32 v20, 3, v98
	v_cmp_ge_i32_e32 vcc, v20, v91
	v_and_b32_e32 v97, 0xffff0000, v6
	v_lshlrev_b32_e32 v6, 16, v6
	v_cndmask_b32_e32 v21, 0, v21, vcc
	v_cmp_lt_i32_e32 vcc, v98, v99
	s_or_b64 s[4:5], s[40:41], vcc
	v_cndmask_b32_e64 v14, v14, 0, s[4:5]
	v_cmp_lt_i32_e32 vcc, v18, v99
	v_cvt_pk_bf16_f32 v21, v21, v157
	ds_write_b16 v74, v21 offset:432
	v_cvt_pk_bf16_f32 v14, v14, v157
	s_or_b64 s[4:5], s[40:41], vcc
	ds_write_b16 v74, v14 offset:32
	v_cndmask_b32_e64 v14, v15, 0, s[4:5]
	v_cmp_lt_i32_e32 vcc, v19, v99
	v_cvt_pk_bf16_f32 v14, v14, v157
	s_or_b64 s[4:5], s[40:41], vcc
	ds_write_b16 v74, v14 offset:176
	v_cndmask_b32_e64 v14, v16, 0, s[4:5]
	v_cmp_lt_i32_e32 vcc, v20, v99
	v_cvt_pk_bf16_f32 v14, v14, v157
	s_or_b64 s[4:5], s[40:41], vcc
	ds_write_b16 v74, v14 offset:320
	v_cndmask_b32_e64 v14, v17, 0, s[4:5]
	v_cvt_pk_bf16_f32 v14, v14, v157
	ds_write_b16 v74, v14 offset:464
	v_or_b32_e32 v14, 32, v91
	v_cmp_lt_i32_e32 vcc, v98, v14
	s_or_b64 s[4:5], s[6:7], vcc
	v_cndmask_b32_e64 v15, v30, 0, s[4:5]
	v_cmp_lt_i32_e32 vcc, v18, v14
	v_cvt_pk_bf16_f32 v15, v15, v157
	s_or_b64 s[4:5], s[6:7], vcc
	ds_write_b16 v74, v15 offset:64
	v_cndmask_b32_e64 v15, v31, 0, s[4:5]
	v_cmp_lt_i32_e32 vcc, v19, v14
	v_cvt_pk_bf16_f32 v15, v15, v157
	s_or_b64 s[4:5], s[6:7], vcc
	v_cmp_lt_i32_e32 vcc, v20, v14
	ds_write_b16 v74, v15 offset:208
	v_cndmask_b32_e64 v15, v32, 0, s[4:5]
	s_or_b64 s[4:5], s[6:7], vcc
	v_readlane_b32 s6, v252, 52
	v_cndmask_b32_e64 v14, v33, 0, s[4:5]
	v_cmp_lt_i32_e32 vcc, v98, v22
	v_readlane_b32 s7, v252, 53
	v_cvt_pk_bf16_f32 v15, v15, v157
	ds_write_b16 v74, v15 offset:352
	v_cvt_pk_bf16_f32 v14, v14, v157
	s_or_b64 s[4:5], s[6:7], vcc
	ds_write_b16 v74, v14 offset:496
	v_cndmask_b32_e64 v14, v34, 0, s[4:5]
	v_cmp_lt_i32_e32 vcc, v18, v22
	v_cvt_pk_bf16_f32 v14, v14, v157
	s_or_b64 s[4:5], s[6:7], vcc
	ds_write_b16 v74, v14 offset:96
	v_cndmask_b32_e64 v14, v35, 0, s[4:5]
	v_cmp_lt_i32_e32 vcc, v19, v22
	v_cvt_pk_bf16_f32 v14, v14, v157
	s_or_b64 s[4:5], s[6:7], vcc
	ds_write_b16 v74, v14 offset:240
	v_cndmask_b32_e64 v14, v36, 0, s[4:5]
	v_cmp_lt_i32_e32 vcc, v20, v22
	v_cvt_pk_bf16_f32 v14, v14, v157
	s_or_b64 s[4:5], s[6:7], vcc
	v_sub_f32_e32 v15, v40, v38
	ds_write_b16 v74, v14 offset:384
	v_cndmask_b32_e64 v14, v37, 0, s[4:5]
	v_mul_f32_e32 v15, 0x3fb8aa3b, v15
	v_cvt_pk_bf16_f32 v14, v14, v157
	v_exp_f32_e32 v15, v15
	ds_write_b16 v74, v14 offset:528
	v_mul_u32_u24_e32 v14, 0x48, v73
	v_add_lshl_u32 v14, v14, v72, 1
	s_waitcnt lgkmcnt(0)
	s_barrier
	v_cvt_pk_bf16_f32 v6, v6, v157
	v_add_u32_e32 v16, v71, v14
	ds_write_b16 v16, v6
	v_mul_f32_e32 v6, v90, v15
	v_sub_f32_e32 v15, v41, v39
	v_mul_f32_e32 v15, 0x3fb8aa3b, v15
	v_exp_f32_e32 v15, v15
	v_cvt_pk_bf16_f32 v6, v6, v157
	v_add_u32_e32 v14, v70, v14
	ds_write_b16 v14, v6
	v_cvt_pk_bf16_f32 v6, v97, v157
	ds_write_b16 v16, v6 offset:144
	v_mul_f32_e32 v6, v89, v15
	v_sub_f32_e32 v15, v44, v42
	v_mul_f32_e32 v15, 0x3fb8aa3b, v15
	v_and_b32_e32 v29, 0xffff0000, v7
	v_lshlrev_b32_e32 v7, 16, v7
	v_cvt_pk_bf16_f32 v6, v6, v157
	v_exp_f32_e32 v15, v15
	ds_write_b16 v14, v6 offset:144
	v_cvt_pk_bf16_f32 v6, v7, v157
	v_sub_f32_e32 v7, v45, v43
	v_mul_f32_e32 v7, 0x3fb8aa3b, v7
	v_exp_f32_e32 v7, v7
	ds_write_b16 v16, v6 offset:288
	v_mul_f32_e32 v6, v88, v15
	v_cvt_pk_bf16_f32 v6, v6, v157
	ds_write_b16 v14, v6 offset:288
	v_cvt_pk_bf16_f32 v6, v29, v157
	ds_write_b16 v16, v6 offset:432
	v_mul_f32_e32 v6, v87, v7
	v_sub_f32_e32 v7, v48, v46
	v_mul_f32_e32 v7, 0x3fb8aa3b, v7
	v_exp_f32_e32 v7, v7
	v_cvt_pk_bf16_f32 v6, v6, v157
	v_and_b32_e32 v28, 0xffff0000, v8
	v_lshlrev_b32_e32 v8, 16, v8
	ds_write_b16 v14, v6 offset:432
	v_cvt_pk_bf16_f32 v6, v8, v157
	ds_write_b16 v16, v6 offset:576
	v_mul_f32_e32 v6, v86, v7
	v_sub_f32_e32 v7, v49, v47
	v_mul_f32_e32 v7, 0x3fb8aa3b, v7
	v_exp_f32_e32 v7, v7
	v_cvt_pk_bf16_f32 v6, v6, v157
	ds_write_b16 v14, v6 offset:576
	v_cvt_pk_bf16_f32 v6, v28, v157
	ds_write_b16 v16, v6 offset:720
	v_mul_f32_e32 v6, v85, v7
	v_sub_f32_e32 v7, v52, v50
	v_mul_f32_e32 v7, 0x3fb8aa3b, v7
	v_exp_f32_e32 v7, v7
	v_cvt_pk_bf16_f32 v6, v6, v157
	v_and_b32_e32 v27, 0xffff0000, v9
	v_lshlrev_b32_e32 v9, 16, v9
	ds_write_b16 v14, v6 offset:720
	v_cvt_pk_bf16_f32 v6, v9, v157
	ds_write_b16 v16, v6 offset:864
	v_mul_f32_e32 v6, v84, v7
	v_sub_f32_e32 v7, v53, v51
	v_mul_f32_e32 v7, 0x3fb8aa3b, v7
	v_exp_f32_e32 v7, v7
	v_cvt_pk_bf16_f32 v6, v6, v157
	ds_write_b16 v14, v6 offset:864
	v_cvt_pk_bf16_f32 v6, v27, v157
	ds_write_b16 v16, v6 offset:1008
	v_mul_f32_e32 v6, v83, v7
	v_sub_f32_e32 v7, v56, v54
	v_mul_f32_e32 v7, 0x3fb8aa3b, v7
	v_exp_f32_e32 v7, v7
	v_cvt_pk_bf16_f32 v6, v6, v157
	s_waitcnt vmcnt(2)
; __device__ __forceinline__ unsigned pk2(float lo, float hi) { return pg8::cvt_pk_bf16(lo, hi); }
; __device__ __forceinline__ bf16_t f2bf(float f) { return (bf16_t)(pk2(f, 0.f) & 0xffffu); }
; __device__ __forceinline__ float fexp(float x) { return __expf(x); }
; #define LBAR() do { asm volatile("s_waitcnt lgkmcnt(0)" ::: "memory"); __builtin_amdgcn_s_barrier(); asm volatile("" ::: "memory"); } while (0)
; __device__ __forceinline__ void store_oloc(bf16_t* oloc, int uid, int w4, int lane, const f32x4 (&acc)[4]) {
;     u32x4* p = (u32x4*)(oloc + ((size_t)uid * 4 + w4) * 1024 + lane * 16);
;     u32x4 a, b;
;     a.x = pk2(acc[0][0], acc[0][1]); a.y = pk2(acc[0][2], acc[0][3]); a.z = pk2(acc[1][0], acc[1][1]); a.w = pk2(acc[1][2], acc[1][3]);
;     b.x = pk2(acc[2][0], acc[2][1]); b.y = pk2(acc[2][2], acc[2][3]); b.z = pk2(acc[3][0], acc[3][1]); b.w = pk2(acc[3][2], acc[3][3]);
;     __builtin_nontemporal_store(a, p); __builtin_nontemporal_store(b, p + 1);
; }
; __device__ __forceinline__ void store_bc(bf16_t* bcs, int uid, int w4, int r, int q, const f32x4 (&acc)[4]) {
; #pragma unroll
;     for (int ct = 0; ct < 4; ++ct) { u32x2 w; w.x = pk2(acc[ct][0], acc[ct][1]); w.y = pk2(acc[ct][2], acc[ct][3]);
;         *(u32x2*)(bcs + (size_t)uid * 4096 + ((ct * 4 + w4) * 64 + q * 16 + r) * 4) = w; }
; }
; __device__ __forceinline__ void hgrn_unit(const Ctx& X, LAS unsigned char* hl, int b, int c, int h, int tid_h, int w4, int lane, int layer) {
;     ...
;         for (int e = 0; e < 16; ++e) { VT[(ds + e) * LT + i] = f2bf(vv[e]); KDT[(ds + e) * LT + i] = f2bf(kk[e] * fexp(G63[e] - Gi[e])); }
;     }
;     LBAR();
; #pragma unroll
;     for (int ct = 0; ct < 4; ++ct) acc[ct] = mma16(QT, 16 * w4, VT, 16 * ct, (f32x4){0.f, 0.f, 0.f, 0.f}, r, q);
;     store_oloc(WSP(bf16_t, WS_OLOC), uid, w4, lane, acc);
; #pragma unroll
;     for (int ct = 0; ct < 4; ++ct) acc[ct] = mma16(KDT, 16 * w4, VT, 16 * ct, (f32x4){0.f, 0.f, 0.f, 0.f}, r, q);
;     store_bc(WSP(bf16_t, WS_BCS), uid, w4, r, q, acc);
	v_and_b32_e32 v26, 0xffff0000, v10
	v_lshlrev_b32_e32 v10, 16, v10
	ds_write_b16 v14, v6 offset:1008
	v_cvt_pk_bf16_f32 v6, v10, v157
	ds_write_b16 v16, v6 offset:1152
	v_mul_f32_e32 v6, v82, v7
	v_sub_f32_e32 v7, v57, v55
	v_mul_f32_e32 v7, 0x3fb8aa3b, v7
	v_exp_f32_e32 v7, v7
	v_cvt_pk_bf16_f32 v6, v6, v157
	ds_write_b16 v14, v6 offset:1152
	v_cvt_pk_bf16_f32 v6, v26, v157
	ds_write_b16 v16, v6 offset:1296
	v_mul_f32_e32 v6, v81, v7
	v_sub_f32_e32 v7, v60, v58
	v_mul_f32_e32 v7, 0x3fb8aa3b, v7
	v_exp_f32_e32 v7, v7
	v_cvt_pk_bf16_f32 v6, v6, v157
	v_and_b32_e32 v25, 0xffff0000, v11
	v_lshlrev_b32_e32 v11, 16, v11
	ds_write_b16 v14, v6 offset:1296
	v_cvt_pk_bf16_f32 v6, v11, v157
	ds_write_b16 v16, v6 offset:1440
	v_mul_f32_e32 v6, v80, v7
	v_sub_f32_e32 v7, v61, v59
	v_mul_f32_e32 v7, 0x3fb8aa3b, v7
	v_exp_f32_e32 v7, v7
	v_cvt_pk_bf16_f32 v6, v6, v157
	ds_write_b16 v14, v6 offset:1440
	v_cvt_pk_bf16_f32 v6, v25, v157
	ds_write_b16 v16, v6 offset:1584
	v_mul_f32_e32 v6, v79, v7
	v_sub_f32_e32 v7, v64, v62
	v_mul_f32_e32 v7, 0x3fb8aa3b, v7
	v_exp_f32_e32 v7, v7
	v_cvt_pk_bf16_f32 v6, v6, v157
	v_and_b32_e32 v24, 0xffff0000, v12
	v_lshlrev_b32_e32 v12, 16, v12
	ds_write_b16 v14, v6 offset:1584
	v_cvt_pk_bf16_f32 v6, v12, v157
	ds_write_b16 v16, v6 offset:1728
	v_mul_f32_e32 v6, v78, v7
	v_sub_f32_e32 v7, v65, v63
	v_mul_f32_e32 v7, 0x3fb8aa3b, v7
	v_exp_f32_e32 v7, v7
	v_cvt_pk_bf16_f32 v6, v6, v157
	ds_write_b16 v14, v6 offset:1728
	v_cvt_pk_bf16_f32 v6, v24, v157
	ds_write_b16 v16, v6 offset:1872
	v_mul_f32_e32 v6, v77, v7
	v_sub_f32_e32 v7, v68, v66
	v_mul_f32_e32 v7, 0x3fb8aa3b, v7
	v_exp_f32_e32 v7, v7
	v_cvt_pk_bf16_f32 v6, v6, v157
	v_and_b32_e32 v23, 0xffff0000, v13
	v_lshlrev_b32_e32 v13, 16, v13
	ds_write_b16 v14, v6 offset:1872
	v_cvt_pk_bf16_f32 v6, v13, v157
	ds_write_b16 v16, v6 offset:2016
	v_mul_f32_e32 v6, v76, v7
	v_sub_f32_e32 v7, v69, v67
	v_mul_f32_e32 v7, 0x3fb8aa3b, v7
	v_exp_f32_e32 v7, v7
	v_cvt_pk_bf16_f32 v6, v6, v157
	ds_write_b16 v14, v6 offset:2016
	v_cvt_pk_bf16_f32 v6, v23, v157
	ds_write_b16 v16, v6 offset:2160
	v_mul_f32_e32 v6, v75, v7
	v_cvt_pk_bf16_f32 v6, v6, v157
	ds_write_b16 v14, v6 offset:2160
	s_waitcnt lgkmcnt(0)
	s_barrier
	v_add_u32_e32 v22, v71, v92
	v_add_u32_e32 v44, v22, v95
	v_mad_u32_u24 v34, v99, s44, v22
	v_mul_u32_u24_e32 v26, 0x90, v93
	v_add3_u32 v18, v70, v26, v92
	ds_read_b128 v[46:49], v94
	ds_read_b128 v[50:53], v94 offset:64
	ds_read_b128 v[54:57], v44
	ds_read_b128 v[58:61], v44 offset:64
	ds_read_b128 v[62:65], v34
	ds_read_b128 v[66:69], v34 offset:64
	ds_read_b128 v[72:75], v34 offset:2304
	ds_read_b128 v[76:79], v34 offset:2368
	ds_read_b128 v[80:83], v44 offset:6912
	ds_read_b128 v[102:105], v44 offset:6976
	ds_read_b128 v[134:137], v18
	ds_read_b128 v[138:141], v18 offset:64
	s_add_u32 s4, s79, s0
	s_addc_u32 s5, s80, s1
	s_add_u32 s0, s74, s0
	s_addc_u32 s1, s75, s1
	v_lshlrev_b32_e32 v42, 4, v130
	v_ashrrev_i32_e32 v43, 31, v42
	v_lshl_add_u64 v[38:39], v[42:43], 1, s[4:5]
	v_lshl_or_b32 v12, v91, 2, s81
	v_lshl_add_u32 v12, v96, 6, v12
	v_ashrrev_i32_e32 v13, 31, v12
	v_lshl_add_u64 v[14:15], v[12:13], 1, s[0:1]
	v_add_u32_e32 v16, 0x800, v12
	v_ashrrev_i32_e32 v17, 31, v16
	v_lshl_add_u64 v[16:17], v[16:17], 1, s[0:1]
	v_add_u32_e32 v20, 0xc00, v12
	v_ashrrev_i32_e32 v21, 31, v20
	v_lshl_add_u64 v[20:21], v[20:21], 1, s[0:1]
	s_waitcnt lgkmcnt(2)
	v_mfma_f32_16x16x32_bf16 v[186:189], v[46:49], v[54:57], 0
	v_mfma_f32_16x16x32_bf16 v[190:193], v[46:49], v[62:65], 0
	v_mfma_f32_16x16x32_bf16 v[194:197], v[46:49], v[72:75], 0
	v_mfma_f32_16x16x32_bf16 v[198:201], v[46:49], v[80:83], 0
	v_mfma_f32_16x16x32_bf16 v[186:189], v[50:53], v[58:61], v[186:189]
	v_mfma_f32_16x16x32_bf16 v[190:193], v[50:53], v[66:69], v[190:193]
	v_mfma_f32_16x16x32_bf16 v[194:197], v[50:53], v[76:79], v[194:197]
	v_mfma_f32_16x16x32_bf16 v[198:201], v[50:53], v[102:105], v[198:201]
	s_waitcnt lgkmcnt(0)
	v_mfma_f32_16x16x32_bf16 v[202:205], v[134:137], v[54:57], 0
	v_mfma_f32_16x16x32_bf16 v[206:209], v[134:137], v[62:65], 0
	v_mfma_f32_16x16x32_bf16 v[210:213], v[134:137], v[72:75], 0
	v_mfma_f32_16x16x32_bf16 v[214:217], v[134:137], v[80:83], 0
	v_mfma_f32_16x16x32_bf16 v[202:205], v[138:141], v[58:61], v[202:205]
	v_mfma_f32_16x16x32_bf16 v[206:209], v[138:141], v[66:69], v[206:209]
	v_mfma_f32_16x16x32_bf16 v[210:213], v[138:141], v[76:79], v[210:213]
	v_mfma_f32_16x16x32_bf16 v[214:217], v[138:141], v[102:105], v[214:217]
	v_cvt_pk_bf16_f32 v218, v186, v187
	v_cvt_pk_bf16_f32 v219, v188, v189
	v_cvt_pk_bf16_f32 v220, v190, v191
	v_cvt_pk_bf16_f32 v221, v192, v193
	v_cvt_pk_bf16_f32 v236, v194, v195
	v_cvt_pk_bf16_f32 v237, v196, v197
	v_cvt_pk_bf16_f32 v238, v198, v199
	v_cvt_pk_bf16_f32 v239, v200, v201
	global_store_dwordx4 v[38:39], v[218:221], off nt
	global_store_dwordx4 v[38:39], v[236:239], off offset:16 nt
	v_cvt_pk_bf16_f32 v246, v202, v203
	v_cvt_pk_bf16_f32 v247, v204, v205
	v_cvt_pk_bf16_f32 v248, v206, v207
	v_cvt_pk_bf16_f32 v249, v208, v209
	v_cvt_pk_bf16_f32 v250, v210, v211
	v_cvt_pk_bf16_f32 v251, v212, v213
	v_cvt_pk_bf16_f32 v226, v214, v215
	v_cvt_pk_bf16_f32 v227, v216, v217
	global_store_dwordx2 v[14:15], v[246:247], off
	global_store_dwordx2 v[14:15], v[248:249], off offset:2048
	global_store_dwordx2 v[16:17], v[250:251], off
	global_store_dwordx2 v[20:21], v[226:227], off
	s_branch .Lhgrn_fin_pad
	s_nop 0
	s_nop 0
	s_nop 0
	s_nop 0
	s_nop 0
	s_nop 0
	s_nop 0
	s_nop 0
	s_nop 0
	s_nop 0
	s_nop 0
	s_nop 0
	s_nop 0
	s_nop 0
	s_nop 0
	s_nop 0
	s_nop 0
	s_nop 0
	s_nop 0
	s_nop 0
	s_nop 0
	s_nop 0
	s_nop 0
	s_nop 0
	s_nop 0
	s_nop 0
	s_nop 0
	s_nop 0
	s_nop 0
	s_nop 0
	s_nop 0
	s_nop 0
.Lhgrn_fin_pad:
	s_waitcnt lgkmcnt(0)
	s_barrier
	s_mov_b64 s[0:1], 0
.LBB0_318:
	s_and_b64 vcc, exec, s[0:1]
	s_cbranch_vccz .LBB0_356
	v_cmp_gt_i32_e32 vcc, 64, v132
	s_and_saveexec_b64 s[94:95], vcc
	s_cbranch_execz .Lgba_early_done
	s_lshl_b32 s98, s21, 6
	s_lshl_b32 s99, s24, 13
	s_or_b32 s98, s98, s99
	s_mov_b32 s99, s17
	v_mov_b32_e32 v240, v132
	v_ashrrev_i32_e32 v241, 31, v132
	v_readlane_b32 s100, v252, 31
	v_readlane_b32 s101, v252, 32
	v_lshl_add_u64 v[240:241], v[240:241], 0, s[98:99]
	v_lshlrev_b64 v[240:241], 5, v[240:241]
	s_lshl_b32 s98, s23, 2
	v_lshl_add_u64 v[240:241], s[100:101], 0, v[240:241]
	v_lshl_add_u64 v[240:241], v[240:241], 0, s[98:99]
	s_add_i32 s98, s23, s14
	s_lshl_b64 s[98:99], s[98:99], 2
	v_readlane_b32 s100, v253, 40
	v_readlane_b32 s101, v253, 41
	v_readlane_b32 s82, v253, 42
	v_readlane_b32 s83, v253, 43
	s_add_u32 s100, s100, s98
	s_addc_u32 s101, s101, s99
	s_add_u32 s82, s82, s98
	s_addc_u32 s83, s83, s99
	global_load_dword v242, v[240:241], off
	global_load_dword v243, v[240:241], off offset:16
	global_load_dword v244, v157, s[100:101]
	global_load_dword v245, v157, s[82:83]

; __device__ __forceinline__ bf16_t f2bf(float f) { return (bf16_t)(pk2(f, 0.f) & 0xffffu); }
; __device__ __forceinline__ float fexp(float x) { return __expf(x); }
; #define LBAR() do { asm volatile("s_waitcnt lgkmcnt(0)" ::: "memory"); __builtin_amdgcn_s_barrier(); asm volatile("" ::: "memory"); } while (0)
; __device__ __forceinline__ void ret_unit(const Ctx& X, LAS unsigned char* hl, int b, int c, int h, int tid_h, int w4, int lane) {
;     ...
;     f32x4 acc[4];
; #pragma unroll
;     for (int ct = 0; ct < 4; ++ct) acc[ct] = mma16(QR, 16 * w4, KR, 16 * ct, (f32x4){0.f, 0.f, 0.f, 0.f}, r, q);
; #pragma unroll
;     for (int ct = 0; ct < 4; ++ct)
; #pragma unroll
;         for (int j = 0; j < 4; ++j) { const int ii = 16 * w4 + 4 * q + j, col = 16 * ct + r;
;             P[ii * LT + col] = f2bf(ii >= col ? acc[ct][j] * fexp(lg * (float)(ii - col)) : 0.f); }
;     LBAR();
.LpfR_done:
	v_or_b32_e32 v6, s39, v32
	v_mul_u32_u24_e32 v19, 0x90, v6
	v_add3_u32 v10, v37, v19, v20
	v_mad_u32_u24 v14, v32, s44, v29
	ds_read_b128 v[6:9], v10
	ds_read_b128 v[38:41], v10 offset:64
	ds_read_b128 v[10:13], v14
	ds_read_b128 v[14:17], v14 offset:64
	s_waitcnt lgkmcnt(1)
	v_mfma_f32_16x16x32_bf16 v[10:13], v[6:9], v[10:13], 0
	v_ashrrev_i32_e32 v18, 4, v130
	v_or_b32_e32 v31, 16, v32
	v_or_b32_e32 v28, 32, v32
	s_waitcnt lgkmcnt(0)
	v_mfma_f32_16x16x32_bf16 v[42:45], v[38:41], v[14:17], v[10:13]
	s_add_u32 s4, s79, s0
	s_addc_u32 s5, s80, s1
	s_add_u32 s0, s74, s0
	v_mov_b32_e32 v10, 0x900
	v_mad_u32_u24 v21, v32, s44, v10
	v_add_u32_e32 v14, v29, v21
	ds_read_b128 v[10:13], v14
	ds_read_b128 v[14:17], v14 offset:64
	s_waitcnt lgkmcnt(1)
	v_mfma_f32_16x16x32_bf16 v[10:13], v[6:9], v[10:13], 0
	s_addc_u32 s1, s75, s1
	s_waitcnt lgkmcnt(0)
	v_mfma_f32_16x16x32_bf16 v[14:17], v[38:41], v[14:17], v[10:13]
	s_nop 4
	v_mov_b32_e32 v10, 0x1200
	v_mad_u32_u24 v22, v32, s44, v10
	v_add_u32_e32 v23, v29, v22
	ds_read_b128 v[10:13], v23
	ds_read_b128 v[24:27], v23 offset:64
	s_waitcnt lgkmcnt(1)
	v_mfma_f32_16x16x32_bf16 v[10:13], v[6:9], v[10:13], 0
	v_mov_b32_e32 v23, 0x1b00
	v_mad_u32_u24 v23, v32, s44, v23
	s_waitcnt lgkmcnt(0)
	v_mfma_f32_16x16x32_bf16 v[10:13], v[38:41], v[24:27], v[10:13]
	v_lshl_add_u32 v27, v18, 2, s39
	v_sub_u32_e32 v26, v27, v32
	v_cvt_f32_i32_e32 v26, v26
	v_add_u32_e32 v25, v29, v23
	ds_read_b128 v[46:49], v25
	v_cmp_ge_i32_e32 vcc, v27, v32
	v_mul_f32_e32 v26, v36, v26
	v_mul_f32_e32 v26, 0x3fb8aa3b, v26
	v_exp_f32_e32 v26, v26
	s_waitcnt lgkmcnt(0)
	v_mfma_f32_16x16x32_bf16 v[6:9], v[6:9], v[46:49], 0
	ds_read_b128 v[46:49], v25 offset:64
	v_lshlrev_b32_e32 v25, 1, v32
	v_mul_f32_e32 v26, v26, v42
	v_cndmask_b32_e32 v26, 0, v26, vcc
	v_mul_lo_u32 v29, v27, s44
	v_cvt_pk_bf16_f32 v26, v26, v157
	v_add3_u32 v25, v35, v25, v29
	v_or_b32_e32 v30, 1, v27
	ds_write_b16 v25, v26
	v_sub_u32_e32 v26, v30, v32
	v_cvt_f32_i32_e32 v26, v26
	v_cmp_ge_i32_e32 vcc, v30, v32
	v_or_b32_e32 v29, 2, v27
	v_or_b32_e32 v24, 48, v32
	v_mul_f32_e32 v26, v36, v26
	v_mul_f32_e32 v26, 0x3fb8aa3b, v26
	v_exp_f32_e32 v26, v26
	s_waitcnt lgkmcnt(1)
	v_mfma_f32_16x16x32_bf16 v[6:9], v[38:41], v[46:49], v[6:9]
	v_add_u32_e32 v38, v34, v20
	v_mad_u32_u24 v39, v32, s44, v38
	v_mul_f32_e32 v26, v26, v43
	v_cndmask_b32_e32 v26, 0, v26, vcc
	v_cvt_pk_bf16_f32 v26, v26, v157
	ds_write_b16 v25, v26 offset:144
	v_sub_u32_e32 v26, v29, v32
	v_cvt_f32_i32_e32 v26, v26
	v_cmp_ge_i32_e32 vcc, v29, v32
	v_add_u32_e32 v40, v38, v21
	v_add_u32_e32 v41, v38, v22
	v_mul_f32_e32 v26, v36, v26
	v_mul_f32_e32 v26, 0x3fb8aa3b, v26
	v_exp_f32_e32 v26, v26
	v_add_u32_e32 v38, v38, v23
	v_mul_f32_e32 v26, v26, v44
	v_cndmask_b32_e32 v26, 0, v26, vcc
	v_cvt_pk_bf16_f32 v26, v26, v157
	ds_write_b16 v25, v26 offset:288
	v_or_b32_e32 v26, 3, v27
	v_sub_u32_e32 v37, v26, v32
	v_cvt_f32_i32_e32 v37, v37
	v_cmp_ge_i32_e32 vcc, v26, v32
	v_mul_f32_e32 v37, v36, v37
	v_mul_f32_e32 v37, 0x3fb8aa3b, v37
	v_exp_f32_e32 v37, v37
	s_nop 0
	v_mul_f32_e32 v37, v37, v45
	v_cndmask_b32_e32 v37, 0, v37, vcc
	v_cvt_pk_bf16_f32 v37, v37, v157
	ds_write_b16 v25, v37 offset:432
	v_sub_u32_e32 v37, v27, v31
	v_cvt_f32_i32_e32 v37, v37
	v_cmp_ge_i32_e32 vcc, v27, v31
	v_mul_f32_e32 v37, v36, v37
	v_mul_f32_e32 v37, 0x3fb8aa3b, v37
	v_exp_f32_e32 v37, v37
	s_nop 0
	v_mul_f32_e32 v14, v37, v14
	v_cndmask_b32_e32 v14, 0, v14, vcc
	v_cvt_pk_bf16_f32 v14, v14, v157
	ds_write_b16 v25, v14 offset:32
	v_sub_u32_e32 v14, v30, v31
	v_cvt_f32_i32_e32 v14, v14
	v_cmp_ge_i32_e32 vcc, v30, v31
	v_mul_f32_e32 v14, v36, v14
	v_mul_f32_e32 v14, 0x3fb8aa3b, v14
	v_exp_f32_e32 v14, v14
	s_nop 0
	v_mul_f32_e32 v14, v14, v15
	v_cndmask_b32_e32 v14, 0, v14, vcc
	v_cvt_pk_bf16_f32 v14, v14, v157
	ds_write_b16 v25, v14 offset:176
	v_sub_u32_e32 v14, v29, v31
	v_cvt_f32_i32_e32 v14, v14
	v_cmp_ge_i32_e32 vcc, v29, v31
	v_mul_f32_e32 v14, v36, v14
	v_mul_f32_e32 v14, 0x3fb8aa3b, v14
	v_exp_f32_e32 v14, v14
	s_nop 0
	v_mul_f32_e32 v14, v14, v16
	v_cndmask_b32_e32 v14, 0, v14, vcc
	v_cvt_pk_bf16_f32 v14, v14, v157
	ds_write_b16 v25, v14 offset:320
	v_sub_u32_e32 v14, v26, v31
	v_cvt_f32_i32_e32 v14, v14
	v_cmp_ge_i32_e32 vcc, v26, v31
	v_mul_f32_e32 v14, v36, v14
	v_mul_f32_e32 v14, 0x3fb8aa3b, v14
	v_exp_f32_e32 v14, v14
	s_nop 0
	v_mul_f32_e32 v14, v14, v17
	v_cndmask_b32_e32 v14, 0, v14, vcc
	v_cvt_pk_bf16_f32 v14, v14, v157
	ds_write_b16 v25, v14 offset:464
	v_sub_u32_e32 v14, v27, v28
	v_cvt_f32_i32_e32 v14, v14
	v_cmp_ge_i32_e32 vcc, v27, v28
	v_mul_f32_e32 v14, v36, v14
	v_mul_f32_e32 v14, 0x3fb8aa3b, v14
	v_exp_f32_e32 v14, v14
	s_nop 0
	v_mul_f32_e32 v10, v14, v10
	v_cndmask_b32_e32 v10, 0, v10, vcc
	v_cvt_pk_bf16_f32 v10, v10, v157
	ds_write_b16 v25, v10 offset:64
	v_sub_u32_e32 v10, v30, v28
	v_cvt_f32_i32_e32 v10, v10
	v_cmp_ge_i32_e32 vcc, v30, v28
	v_mul_f32_e32 v10, v36, v10
	v_mul_f32_e32 v10, 0x3fb8aa3b, v10
	v_exp_f32_e32 v10, v10
	s_nop 0
	v_mul_f32_e32 v10, v10, v11
	v_cndmask_b32_e32 v10, 0, v10, vcc
	v_cvt_pk_bf16_f32 v10, v10, v157
	ds_write_b16 v25, v10 offset:208
	v_sub_u32_e32 v10, v29, v28
	v_cvt_f32_i32_e32 v10, v10
	v_cmp_ge_i32_e32 vcc, v29, v28
	v_mul_f32_e32 v10, v36, v10
	v_mul_f32_e32 v10, 0x3fb8aa3b, v10
	v_exp_f32_e32 v10, v10
	s_nop 0
	v_mul_f32_e32 v10, v10, v12
	v_cndmask_b32_e32 v10, 0, v10, vcc
	v_cvt_pk_bf16_f32 v10, v10, v157
	ds_write_b16 v25, v10 offset:352
	v_sub_u32_e32 v10, v26, v28
	v_cvt_f32_i32_e32 v10, v10
	v_cmp_ge_i32_e32 vcc, v26, v28
	v_mul_f32_e32 v10, v36, v10
	v_mul_f32_e32 v10, 0x3fb8aa3b, v10
	v_exp_f32_e32 v10, v10
	s_nop 0
	v_mul_f32_e32 v10, v10, v13
	v_cndmask_b32_e32 v10, 0, v10, vcc
	v_cvt_pk_bf16_f32 v10, v10, v157
	ds_write_b16 v25, v10 offset:496
	v_sub_u32_e32 v10, v27, v24
	v_cvt_f32_i32_e32 v10, v10
	v_cmp_ge_i32_e32 vcc, v27, v24
	v_mul_f32_e32 v10, v36, v10
	v_mul_f32_e32 v10, 0x3fb8aa3b, v10
	v_exp_f32_e32 v10, v10
	s_nop 0
	v_mul_f32_e32 v6, v10, v6
	v_cndmask_b32_e32 v6, 0, v6, vcc
	v_cvt_pk_bf16_f32 v6, v6, v157
	ds_write_b16 v25, v6 offset:96
	v_sub_u32_e32 v6, v30, v24
	v_cvt_f32_i32_e32 v6, v6
	v_cmp_ge_i32_e32 vcc, v30, v24
	v_add3_u32 v10, v35, v19, v20
	v_mul_f32_e32 v6, v36, v6
	v_mul_f32_e32 v6, 0x3fb8aa3b, v6
	v_exp_f32_e32 v6, v6
	s_nop 0
	v_mul_f32_e32 v6, v6, v7
	v_cndmask_b32_e32 v6, 0, v6, vcc
	v_cvt_pk_bf16_f32 v6, v6, v157
	ds_write_b16 v25, v6 offset:240
	v_sub_u32_e32 v6, v29, v24
	v_cvt_f32_i32_e32 v6, v6
	v_cmp_ge_i32_e32 vcc, v29, v24
	v_mul_f32_e32 v6, v36, v6
	v_mul_f32_e32 v6, 0x3fb8aa3b, v6
	v_exp_f32_e32 v6, v6
	s_nop 0
	v_mul_f32_e32 v6, v6, v8
	v_cndmask_b32_e32 v6, 0, v6, vcc
	v_cvt_pk_bf16_f32 v6, v6, v157
	ds_write_b16 v25, v6 offset:384
	v_sub_u32_e32 v6, v26, v24
	v_cvt_f32_i32_e32 v6, v6
	v_cmp_ge_i32_e32 vcc, v26, v24
	v_mul_f32_e32 v6, v36, v6
	v_mul_f32_e32 v6, 0x3fb8aa3b, v6
	v_exp_f32_e32 v6, v6
	s_nop 0
	v_mul_f32_e32 v6, v6, v9
	v_cndmask_b32_e32 v6, 0, v6, vcc
	v_cvt_pk_bf16_f32 v6, v6, v157
	ds_write_b16 v25, v6 offset:528
	s_waitcnt lgkmcnt(0)
	s_barrier
; __device__ __forceinline__ unsigned pk2(float lo, float hi) { return pg8::cvt_pk_bf16(lo, hi); }
; #define LBAR() do { asm volatile("s_waitcnt lgkmcnt(0)" ::: "memory"); __builtin_amdgcn_s_barrier(); asm volatile("" ::: "memory"); } while (0)
; __device__ __forceinline__ void store_oloc(bf16_t* oloc, int uid, int w4, int lane, const f32x4 (&acc)[4]) {
;     u32x4* p = (u32x4*)(oloc + ((size_t)uid * 4 + w4) * 1024 + lane * 16);
;     u32x4 a, b;
;     a.x = pk2(acc[0][0], acc[0][1]); a.y = pk2(acc[0][2], acc[0][3]); a.z = pk2(acc[1][0], acc[1][1]); a.w = pk2(acc[1][2], acc[1][3]);
;     b.x = pk2(acc[2][0], acc[2][1]); b.y = pk2(acc[2][2], acc[2][3]); b.z = pk2(acc[3][0], acc[3][1]); b.w = pk2(acc[3][2], acc[3][3]);
;     __builtin_nontemporal_store(a, p); __builtin_nontemporal_store(b, p + 1);
; }
; __device__ __forceinline__ void store_bc(bf16_t* bcs, int uid, int w4, int r, int q, const f32x4 (&acc)[4]) {
; #pragma unroll
;     for (int ct = 0; ct < 4; ++ct) { u32x2 w; w.x = pk2(acc[ct][0], acc[ct][1]); w.y = pk2(acc[ct][2], acc[ct][3]);
;         *(u32x2*)(bcs + (size_t)uid * 4096 + ((ct * 4 + w4) * 64 + q * 16 + r) * 4) = w; }
; }
; __device__ __forceinline__ void ret_unit(const Ctx& X, LAS unsigned char* hl, int b, int c, int h, int tid_h, int w4, int lane) {
;     ...
; #pragma unroll
;     for (int ct = 0; ct < 4; ++ct) acc[ct] = mma16(P, 16 * w4, VT, 16 * ct, (f32x4){0.f, 0.f, 0.f, 0.f}, r, q);
;     store_oloc(WSP(bf16_t, WS_OLOC), uid, w4, lane, acc);
; #pragma unroll
;     for (int ct = 0; ct < 4; ++ct) acc[ct] = mma16(KDT, 16 * w4, VT, 16 * ct, (f32x4){0.f, 0.f, 0.f, 0.f}, r, q);
;     store_bc(WSP(bf16_t, WS_BCS), uid, w4, r, q, acc);
;     LBAR();
	v_add3_u32 v42, v33, v19, v20
	ds_read_b128 v[46:49], v10
	ds_read_b128 v[50:53], v10 offset:64
	ds_read_b128 v[54:57], v39
	ds_read_b128 v[58:61], v39 offset:64
	ds_read_b128 v[62:65], v40
	ds_read_b128 v[66:69], v40 offset:64
	ds_read_b128 v[72:75], v41
	ds_read_b128 v[76:79], v41 offset:64
	ds_read_b128 v[80:83], v38
	ds_read_b128 v[102:105], v38 offset:64
	ds_read_b128 v[134:137], v42
	ds_read_b128 v[138:141], v42 offset:64
	v_lshlrev_b32_e32 v6, 4, v130
	v_ashrrev_i32_e32 v7, 31, v6
	v_lshl_add_u64 v[22:23], v[6:7], 1, s[4:5]
	v_lshl_or_b32 v12, v32, 2, s81
	v_lshl_add_u32 v12, v18, 6, v12
	v_ashrrev_i32_e32 v13, 31, v12
	v_lshl_add_u64 v[14:15], v[12:13], 1, s[0:1]
	v_add_u32_e32 v16, 0x800, v12
	v_ashrrev_i32_e32 v17, 31, v16
	v_lshl_add_u64 v[16:17], v[16:17], 1, s[0:1]
	v_add_u32_e32 v8, 0xc00, v12
	v_ashrrev_i32_e32 v9, 31, v8
	v_lshl_add_u64 v[8:9], v[8:9], 1, s[0:1]
	s_waitcnt lgkmcnt(2)
	v_mfma_f32_16x16x32_bf16 v[186:189], v[46:49], v[54:57], 0
	v_mfma_f32_16x16x32_bf16 v[190:193], v[46:49], v[62:65], 0
	v_mfma_f32_16x16x32_bf16 v[194:197], v[46:49], v[72:75], 0
	v_mfma_f32_16x16x32_bf16 v[198:201], v[46:49], v[80:83], 0
	v_mfma_f32_16x16x32_bf16 v[186:189], v[50:53], v[58:61], v[186:189]
	v_mfma_f32_16x16x32_bf16 v[190:193], v[50:53], v[66:69], v[190:193]
	v_mfma_f32_16x16x32_bf16 v[194:197], v[50:53], v[76:79], v[194:197]
	v_mfma_f32_16x16x32_bf16 v[198:201], v[50:53], v[102:105], v[198:201]
	s_waitcnt lgkmcnt(0)
	v_mfma_f32_16x16x32_bf16 v[202:205], v[134:137], v[54:57], 0
	v_mfma_f32_16x16x32_bf16 v[206:209], v[134:137], v[62:65], 0
	v_mfma_f32_16x16x32_bf16 v[210:213], v[134:137], v[72:75], 0
	v_mfma_f32_16x16x32_bf16 v[214:217], v[134:137], v[80:83], 0
	v_mfma_f32_16x16x32_bf16 v[202:205], v[138:141], v[58:61], v[202:205]
	v_mfma_f32_16x16x32_bf16 v[206:209], v[138:141], v[66:69], v[206:209]
	v_mfma_f32_16x16x32_bf16 v[210:213], v[138:141], v[76:79], v[210:213]
	v_mfma_f32_16x16x32_bf16 v[214:217], v[138:141], v[102:105], v[214:217]
	v_cvt_pk_bf16_f32 v218, v186, v187
	v_cvt_pk_bf16_f32 v219, v188, v189
	v_cvt_pk_bf16_f32 v220, v190, v191
	v_cvt_pk_bf16_f32 v221, v192, v193
	v_cvt_pk_bf16_f32 v236, v194, v195
	v_cvt_pk_bf16_f32 v237, v196, v197
	v_cvt_pk_bf16_f32 v238, v198, v199
	v_cvt_pk_bf16_f32 v239, v200, v201
	global_store_dwordx4 v[22:23], v[218:221], off nt
	global_store_dwordx4 v[22:23], v[236:239], off offset:16 nt
	v_cvt_pk_bf16_f32 v246, v202, v203
	v_cvt_pk_bf16_f32 v247, v204, v205
	v_cvt_pk_bf16_f32 v248, v206, v207
	v_cvt_pk_bf16_f32 v249, v208, v209
	v_cvt_pk_bf16_f32 v250, v210, v211
	v_cvt_pk_bf16_f32 v251, v212, v213
	v_cvt_pk_bf16_f32 v226, v214, v215
	v_cvt_pk_bf16_f32 v227, v216, v217
	global_store_dwordx2 v[14:15], v[246:247], off
	global_store_dwordx2 v[14:15], v[248:249], off offset:2048
	global_store_dwordx2 v[16:17], v[250:251], off
	global_store_dwordx2 v[8:9], v[226:227], off
	s_branch .Lret_fin_pad
	s_nop 0
	s_nop 0
	s_nop 0
	s_nop 0
	s_nop 0
	s_nop 0
	s_nop 0
	s_nop 0
	s_nop 0
	s_nop 0
	s_nop 0
	s_nop 0
	s_nop 0
	s_nop 0
	s_nop 0
	s_nop 0
	s_nop 0
	s_nop 0
	s_nop 0
	s_nop 0
	s_nop 0
	s_nop 0
	s_nop 0
	s_nop 0
	s_nop 0
	s_nop 0
	s_nop 0
.Lret_fin_pad:
	s_waitcnt lgkmcnt(0)
	s_barrier
	s_branch .LBB0_233
